# attention: next-tile LDS store moved ahead of the tile's last eight PV MFMAs (runs under them)
# speedup vs baseline: 1.0064x; 1.0007x over previous
; DEVI unsigned pk2(float lo, float hi) { f32x2 v = {lo, hi}; bf16x2_t b = __builtin_convertvector(v, bf16x2_t); return __builtin_bit_cast(unsigned, b); }
; DEVI void attn_item(const P& p, int item, char* smem) {
;     ...
;                 float mx = s[0][0];
; #pragma unroll
;                 for (int n = 0; n < 4; ++n)
; #pragma unroll
;                     for (int j = 0; j < 4; ++j) mx = fmaxf(mx, s[n][j]);
;                 mx = rowmax4(mx);
;                 const float mnew = fmaxf(mrow[m], mx);
;                 const float alpha = __builtin_amdgcn_exp2f(mrow[m] - mnew);
;                 mrow[m] = mnew;
;                 float ls = 0.f;
; #pragma unroll
;                 for (int n = 0; n < 4; ++n)
; #pragma unroll
;                     for (int j = 0; j < 4; ++j) { s[n][j] = __builtin_amdgcn_exp2f(s[n][j] - mnew); ls += s[n][j]; }
;                 lrow[m] = lrow[m] * alpha + ls;
; #pragma unroll
;                 for (int nd = 0; nd < 4; ++nd) O[nd][m] *= alpha;
; #pragma unroll
;                 for (int kk = 0; kk < 2; ++kk) {
;                     union { uint4 u; bf16x8 v; } cv;
;                     cv.u.x = pk2(s[2 * kk][0], s[2 * kk][1]); cv.u.y = pk2(s[2 * kk][2], s[2 * kk][3]);
;                     cv.u.z = pk2(s[2 * kk + 1][0], s[2 * kk + 1][1]); cv.u.w = pk2(s[2 * kk + 1][2], s[2 * kk + 1][3]);
;                     Pf[m][kk] = cv.v;
;                 }
;             }
; #pragma unroll
;             for (int nd = 0; nd < 4; ++nd)
; #pragma unroll
;                 for (int kk = 0; kk < 2; ++kk) {
;                     const int row = 16 * nd + fr, x2 = 2 * ((row >> 1) & 7);
;                     const uint2 lo = *(const uint2*)(sV + row * 128 + (((8 * kk + fq) ^ x2) << 3));
;                     const uint2 hi = *(const uint2*)(sV + row * 128 + (((8 * kk + 4 + fq) ^ x2) << 3));
;                     union { uint4 u; bf16x8 v; } cv;
;                     cv.u.x = lo.x; cv.u.y = lo.y; cv.u.z = hi.x; cv.u.w = hi.y;
; #pragma unroll
;                     for (int m = 0; m < 2; ++m) O[nd][m] = __builtin_amdgcn_mfma_f32_16x16x32_bf16(cv.v, Pf[m][kk], O[nd][m], 0, 0, 0);
;                 }
.LBB0_1433:
	v_max3_f32 v91, v160, v86, v87
	v_sub_f32_e32 v0, v78, v91
	v_exp_f32_e32 v78, v0
	v_sub_f32_e32 v79, v79, v91
	v_exp_f32_e32 v79, v79
	v_sub_f32_e32 v80, v80, v91
	v_exp_f32_e32 v80, v80
	v_sub_f32_e32 v81, v81, v91
	v_exp_f32_e32 v81, v81
	v_sub_f32_e32 v74, v74, v91
	v_add_f32_e32 v82, 0, v78
	v_exp_f32_e32 v74, v74
	v_sub_f32_e32 v75, v75, v91
	v_add_f32_e32 v82, v79, v82
	v_exp_f32_e32 v75, v75
	v_sub_f32_e32 v76, v76, v91
	v_add_f32_e32 v82, v80, v82
	v_exp_f32_e32 v76, v76
	v_sub_f32_e32 v77, v77, v91
	v_add_f32_e32 v82, v81, v82
	v_exp_f32_e32 v77, v77
	v_sub_f32_e32 v58, v58, v91
	v_add_f32_e32 v82, v74, v82
	v_exp_f32_e32 v58, v58
	v_sub_f32_e32 v59, v59, v91
	v_add_f32_e32 v82, v75, v82
	v_exp_f32_e32 v59, v59
	v_add_f32_e32 v82, v76, v82
	v_add_f32_e32 v82, v77, v82
	v_add_f32_e32 v82, v58, v82
	v_sub_f32_e32 v50, v50, v91
	v_sub_f32_e32 v51, v51, v91
	v_exp_f32_e32 v83, v50
	v_add_f32_e32 v50, v59, v82
	v_exp_f32_e32 v82, v51
	v_sub_f32_e32 v51, v52, v91
	v_cvt_pk_bf16_f32 v52, v74, v75
	v_max_f32_e32 v74, v70, v71
	v_max3_f32 v74, v74, v72, v73
	v_max3_f32 v74, v74, v62, v63
	v_max3_f32 v74, v74, v64, v65
	v_max3_f32 v74, v74, v54, v55
	v_sub_f32_e32 v60, v60, v91
	v_max3_f32 v74, v74, v56, v57
	v_exp_f32_e32 v60, v60
	v_sub_f32_e32 v61, v61, v91
	v_max3_f32 v74, v74, v66, v67
	v_exp_f32_e32 v61, v61
	v_max3_f32 v74, v74, v68, v69
	v_mov_b32_e32 v75, v74
	s_nop 1
	v_permlane32_swap_b32_e32 v74, v75
	v_add_f32_e32 v50, v60, v50
	v_exp_f32_e32 v84, v51
	v_sub_f32_e32 v51, v53, v91
	v_sub_f32_e32 v0, v160, v91
	v_add_f32_e32 v50, v61, v50
	v_exp_f32_e32 v85, v51
	v_max_f32_e32 v74, v74, v75
	v_add_f32_e32 v50, v83, v50
	v_exp_f32_e32 v0, v0
	v_mov_b32_e32 v75, v74
	v_add_f32_e32 v50, v82, v50
	s_nop 0
	v_permlane16_swap_b32_e32 v74, v75
	v_add_f32_e32 v50, v84, v50
	v_max3_f32 v93, v159, v74, v75
	v_add_f32_e32 v92, v85, v50
	v_sub_f32_e32 v54, v54, v93
	v_fmac_f32_e32 v92, v158, v0
	v_exp_f32_e32 v158, v54
	v_sub_f32_e32 v54, v55, v93
	v_sub_f32_e32 v74, v159, v93
	v_exp_f32_e32 v159, v54
	v_sub_f32_e32 v54, v56, v93
	v_exp_f32_e32 v160, v54
	v_sub_f32_e32 v54, v57, v93
	v_sub_f32_e32 v62, v62, v93
	v_exp_f32_e32 v161, v54
	v_sub_f32_e32 v54, v66, v93
	v_exp_f32_e32 v94, v62
	v_sub_f32_e32 v62, v63, v93
	v_exp_f32_e32 v162, v54
	v_sub_f32_e32 v54, v67, v93
	v_exp_f32_e32 v95, v62
	v_sub_f32_e32 v62, v64, v93
	v_exp_f32_e32 v163, v54
	v_sub_f32_e32 v54, v68, v93
	v_exp_f32_e32 v96, v62
	v_sub_f32_e32 v62, v65, v93
	v_exp_f32_e32 v164, v54
	v_sub_f32_e32 v54, v69, v93
	v_exp_f32_e32 v97, v62
	v_exp_f32_e32 v165, v54
	ds_read_b128 v[54:57], v132 offset:8192
	ds_read_b128 v[62:65], v132 offset:10240
	v_sub_f32_e32 v70, v70, v93
	v_exp_f32_e32 v86, v70
	v_sub_f32_e32 v70, v71, v93
	v_exp_f32_e32 v87, v70
	v_sub_f32_e32 v70, v72, v93
	v_cvt_pk_bf16_f32 v50, v78, v79
	v_cvt_pk_bf16_f32 v51, v80, v81
	v_cvt_pk_bf16_f32 v53, v76, v77
	v_exp_f32_e32 v88, v70
	v_sub_f32_e32 v70, v73, v93
	v_exp_f32_e32 v90, v74
	ds_read_b128 v[74:77], v134 offset:8192
	ds_read_b128 v[78:81], v134 offset:10240
	v_exp_f32_e32 v89, v70
	s_waitcnt lgkmcnt(3)
	s_waitcnt lgkmcnt(2)
	v_pk_mul_f32 v[40:41], v[40:41], v[0:1] op_sel_hi:[1,0]
	v_pk_mul_f32 v[38:39], v[38:39], v[0:1] op_sel_hi:[1,0]
	v_pk_mul_f32 v[44:45], v[44:45], v[0:1] op_sel_hi:[1,0]
	v_pk_mul_f32 v[42:43], v[42:43], v[0:1] op_sel_hi:[1,0]
	v_cvt_pk_bf16_f32 v58, v58, v59
	v_cvt_pk_bf16_f32 v59, v60, v61
	v_cvt_pk_bf16_f32 v60, v83, v82
	v_cvt_pk_bf16_f32 v61, v84, v85
	v_pk_mul_f32 v[16:17], v[16:17], v[90:91] op_sel_hi:[1,0]
	v_pk_mul_f32 v[14:15], v[14:15], v[90:91] op_sel_hi:[1,0]
	v_cvt_pk_bf16_f32 v66, v86, v87
	v_cvt_pk_bf16_f32 v67, v88, v89
	v_cvt_pk_bf16_f32 v68, v94, v95
	v_cvt_pk_bf16_f32 v69, v96, v97
	s_waitcnt lgkmcnt(1)
	s_waitcnt lgkmcnt(0)
	v_pk_mul_f32 v[12:13], v[12:13], v[90:91] op_sel_hi:[1,0]
	v_pk_mul_f32 v[10:11], v[10:11], v[90:91] op_sel_hi:[1,0]
	v_pk_mul_f32 v[48:49], v[48:49], v[0:1] op_sel_hi:[1,0]
	v_pk_mul_f32 v[46:47], v[46:47], v[0:1] op_sel_hi:[1,0]
	v_mfma_f32_16x16x32_bf16 v[38:41], v[54:57], v[50:53], v[38:41]
	v_mul_f32_e64 v20, v20, v0
	v_mul_f32_e64 v21, v21, v0
	v_pk_mul_f32 v[18:19], v[18:19], v[0:1] op_sel_hi:[1,0]
	v_add_f32_e32 v0, 0, v86
	v_mfma_f32_16x16x32_bf16 v[14:17], v[54:57], v[66:69], v[14:17]
	ds_read_b128 v[54:57], v132 offset:12288
	v_add_f32_e32 v0, v87, v0
	v_add_f32_e32 v0, v88, v0
	v_mfma_f32_16x16x32_bf16 v[42:45], v[62:65], v[50:53], v[42:45]
	v_cvt_pk_bf16_f32 v70, v158, v159
	v_cvt_pk_bf16_f32 v71, v160, v161
	v_cvt_pk_bf16_f32 v72, v162, v163
	v_mfma_f32_16x16x32_bf16 v[10:13], v[62:65], v[66:69], v[10:13]
	ds_read_b128 v[62:65], v132 offset:14336
	v_cvt_pk_bf16_f32 v73, v164, v165
	v_add_f32_e32 v0, v89, v0
	v_mfma_f32_16x16x32_bf16 v[38:41], v[74:77], v[58:61], v[38:41]
	v_add_f32_e32 v0, v94, v0
	s_waitcnt lgkmcnt(1)
	v_mfma_f32_16x16x32_bf16 v[14:17], v[74:77], v[70:73], v[14:17]
	ds_read_b128 v[74:77], v134 offset:12288
	s_waitcnt lgkmcnt(1)
	v_mfma_f32_16x16x32_bf16 v[42:45], v[78:81], v[58:61], v[42:45]
	v_add_f32_e32 v0, v95, v0
	v_mfma_f32_16x16x32_bf16 v[10:13], v[78:81], v[70:73], v[10:13]
	ds_read_b128 v[78:81], v134 offset:14336
	v_add_f32_e32 v0, v96, v0
	v_add_f32_e32 v0, v97, v0
	v_add_f32_e32 v0, v158, v0
	v_pk_mul_f32 v[8:9], v[8:9], v[90:91] op_sel_hi:[1,0]
	v_pk_mul_f32 v[6:7], v[6:7], v[90:91] op_sel_hi:[1,0]
	s_waitcnt lgkmcnt(0)
	v_xor_b32_e32 v133, 0x4000, v133
	v_xor_b32_e32 v135, 0x4000, v135
	v_xor_b32_e32 v214, 0x4000, v214
	v_xor_b32_e32 v217, 0x4000, v217
	v_xor_b32_e32 v229, 0x4000, v229
	v_xor_b32_e32 v215, 0x4000, v215
	s_cmp_eq_u32 s99, 1
	s_cbranch_scc0 .Lat_endw2
	s_waitcnt vmcnt(0)
	ds_write_b128 v133, v[190:193]
	ds_write_b64 v135, v[194:195] offset:8192
	ds_write_b64 v214, v[196:197] offset:8192
	ds_write_b128 v217, v[198:201]
	ds_write_b64 v229, v[202:203] offset:8192
	ds_write_b64 v215, v[204:205] offset:8192
	s_mov_b32 s99, 2
.Lat_endw2:
	v_add_f32_e32 v0, v159, v0
	v_pk_mul_f32 v[4:5], v[4:5], v[90:91] op_sel_hi:[1,0]
	v_pk_mul_f32 v[2:3], v[2:3], v[90:91] op_sel_hi:[1,0]
	v_mfma_f32_16x16x32_bf16 v[46:49], v[54:57], v[50:53], v[46:49]
	v_add_f32_e32 v0, v160, v0
	v_add_f32_e32 v0, v161, v0
	v_add_f32_e32 v0, v162, v0
	v_mfma_f32_16x16x32_bf16 v[6:9], v[54:57], v[66:69], v[6:9]
	v_add_f32_e32 v0, v163, v0
	v_add_f32_e32 v0, v164, v0
	v_add_f32_e32 v0, v165, v0
	v_mfma_f32_16x16x32_bf16 v[18:21], v[62:65], v[50:53], v[18:21]
	v_fmac_f32_e32 v0, v139, v90
	v_mov_b32_e32 v159, v93
	v_mov_b32_e32 v160, v91
	v_mfma_f32_16x16x32_bf16 v[2:5], v[62:65], v[66:69], v[2:5]
	v_mov_b32_e32 v139, v0
	v_mov_b32_e32 v158, v92
	v_mfma_f32_16x16x32_bf16 v[46:49], v[74:77], v[58:61], v[46:49]
	v_mfma_f32_16x16x32_bf16 v[6:9], v[74:77], v[70:73], v[6:9]
	v_mfma_f32_16x16x32_bf16 v[18:21], v[78:81], v[58:61], v[18:21]
	v_mfma_f32_16x16x32_bf16 v[2:5], v[78:81], v[70:73], v[2:5]
	v_xor_b32_e32 v130, 0x4000, v130
	v_xor_b32_e32 v131, 0x4000, v131
	v_xor_b32_e32 v132, 0x4000, v132
	v_xor_b32_e32 v134, 0x4000, v134
